# scan: priority raise moved to the start of the chunk MFMA block so its LDS fragment reads also issue at priority 1
# speedup vs baseline: 1.0025x; 1.0025x over previous
; #define LAS __attribute__((address_space(3)))
; __device__ __forceinline__ void scan_phase(LAS unsigned char* lds, bf16* proj, int G, int bid) {
;     ...
;             SC_PREP(c + 1);
;             {
;                 const LAS unsigned char* qeb = set + O_QE + fr * QST; const LAS unsigned char* keb = set + O_KE + fr * QST;
;                 bf16x8 kaf[4], qbf[4];
; #pragma unroll
;                 for (int i = 0; i < 4; ++i) { kaf[i] = *(const LAS bf16x8*)(keb + (32 * i + fq * 8) * 2); qbf[i] = *(const LAS bf16x8*)(qeb + (32 * i + fq * 8) * 2); }
;                 u32x2 qlo[4], qhi[4];
; #pragma unroll
;                 for (int i = 0; i < 4; ++i) { qlo[i] = *(const LAS u32x2*)(qeb + (32 * i + fq * 4) * 2); qhi[i] = *(const LAS u32x2*)(qeb + (32 * i + 16 + fq * 4) * 2); }
;                 const bf16x8 vf = *(const LAS bf16x8*)(lds + O_VT + (c % 3) * 8192 + (wave * 16 + fr) * 64 + fq * 16);
;                 f32x4 pt = (f32x4){0.f, 0.f, 0.f, 0.f};
;                 __builtin_amdgcn_s_setprio(1);
; #pragma unroll
;                 for (int i = 0; i < 4; ++i) pt = __builtin_amdgcn_mfma_f32_16x16x32_bf16(kaf[i], qbf[i], pt, 0, 0, 0);
.LBB0_433:
	s_add_i32 s7, s6, 1
	s_bitcmp1_b32 s7, 0
	s_cselect_b32 s0, 0x8600, 0
	s_add_i32 s0, s0, 0
	v_lshl_add_u32 v1, v80, 2, s0
	v_lshl_add_u32 v0, v71, 2, v1
	ds_read2_b32 v[48:49], v0 offset1:132
	v_add_u32_e32 v3, 0x2000, v0
	ds_read2_b32 v[50:51], v3 offset0:64 offset1:196
	v_add_u32_e32 v3, 0x400, v0
	ds_read2_b32 v[98:99], v3 offset0:8 offset1:140
	v_add_u32_e32 v0, 0x2400, v0
	ds_read2_b32 v[100:101], v0 offset0:72 offset1:204
	s_waitcnt lgkmcnt(3)
	v_sub_f32_e32 v0, 1.0, v48
	v_max_f32_e32 v3, 0x3bdb8bac, v0
	v_sub_f32_e32 v0, 1.0, v49
	v_max_f32_e32 v0, 0x3bdb8bac, v0
	v_mul_f32_e32 v65, v3, v0
	s_waitcnt lgkmcnt(1)
	v_sub_f32_e32 v0, 1.0, v98
	v_max_f32_e32 v0, 0x3bdb8bac, v0
	v_mul_f32_e32 v104, v65, v0
	v_sub_f32_e32 v0, 1.0, v99
	v_max_f32_e32 v0, 0x3bdb8bac, v0
	v_mul_f32_e32 v105, v104, v0
	v_add3_u32 v1, v1, v90, v206
	s_nop 0
	v_mul_f32_dpp v0, v105, v105 quad_perm:[0,0,1,2] row_mask:0xf bank_mask:0xf bound_ctrl:1
	v_cndmask_b32_e64 v0, v0, v105, s[44:45]
	s_nop 1
	v_mul_f32_dpp v102, v0, v0 quad_perm:[0,0,0,1] row_mask:0xf bank_mask:0xf bound_ctrl:1
	v_cndmask_b32_e64 v102, v0, v102, s[46:47]
	v_mov_b32_e32 v0, 0
	s_nop 1
	v_mov_b32_dpp v0, v102 quad_perm:[0,0,1,2] row_mask:0xf bank_mask:0xf
	v_cndmask_b32_e64 v106, v0, 1.0, s[44:45]
	v_mov_b32_e32 v0, 0
	v_mul_f32_e32 v3, v3, v106
	s_nop 0
	v_mov_b32_dpp v0, v102 quad_perm:[3,3,3,3] row_mask:0xf bank_mask:0xf
	v_rcp_f32_e32 v102, v3
	v_mul_f32_e32 v3, v50, v3
	v_cvt_pk_bf16_f32 v3, v3, s0
	ds_write_b16 v1, v3 offset:16896
	v_mul_f32_e32 v3, v65, v106
	v_rcp_f32_e32 v103, v3
	v_mul_f32_e32 v3, v51, v3
	v_cvt_pk_bf16_f32 v3, v3, s0
	ds_write_b16 v1, v3 offset:17168
	v_mul_f32_e32 v3, v104, v106
	v_rcp_f32_e32 v50, v3
	s_waitcnt lgkmcnt(2)
	v_mul_f32_e32 v3, v100, v3
	v_cvt_pk_bf16_f32 v3, v3, s0
	ds_write_b16 v1, v3 offset:17440
	v_mul_f32_e32 v3, v105, v106
	v_rcp_f32_e32 v51, v3
	v_mul_f32_e32 v3, v101, v3
	v_cvt_pk_bf16_f32 v3, v3, s0
	v_pk_mul_f32 v[48:49], v[48:49], v[102:103]
	ds_write_b16 v1, v3 offset:17712
	v_cvt_pk_bf16_f32 v3, v48, s0
	ds_write_b16 v1, v3 offset:21248
	v_cvt_pk_bf16_f32 v3, v49, s0
	v_pk_mul_f32 v[50:51], v[98:99], v[50:51]
	ds_write_b16 v1, v3 offset:21520
	v_cvt_pk_bf16_f32 v3, v50, s0
	ds_write_b16 v1, v3 offset:21792
	v_cvt_pk_bf16_f32 v3, v51, s0
	v_pk_mul_f32 v[100:101], v[48:49], v[0:1] op_sel_hi:[1,0]
	v_pk_mul_f32 v[98:99], v[50:51], v[0:1] op_sel_hi:[1,0]
	ds_write_b16 v1, v3 offset:22064
	v_add_u32_e32 v1, s0, v83
	v_cvt_pk_bf16_f32 v48, v100, v101
	v_cvt_pk_bf16_f32 v49, v98, v99
	v_add_u32_e32 v3, v1, v55
	ds_write_b64 v3, v[48:49] offset:25600
	s_and_saveexec_b64 s[0:1], s[44:45]
	v_add_u32_e32 v1, v1, v84
	ds_write_b32 v1, v0 offset:33792
	s_or_b64 exec, exec, s[0:1]
	s_setprio 1
	s_mul_hi_u32 s0, s6, 0xaaaaaaab
	s_lshr_b32 s0, s0, 1
	s_bitcmp1_b32 s6, 0
	s_cselect_b32 s1, 0x8600, 0
	s_add_i32 s14, s1, 0
	v_add_u32_e32 v0, s14, v88
	v_add_u32_e32 v1, v0, v89
	ds_read_b128 v[48:51], v1 offset:21248
	ds_read_b128 v[98:101], v1 offset:21312
	ds_read_b128 v[126:129], v1 offset:16896
	ds_read_b128 v[130:133], v1 offset:16960
	ds_read_b128 v[110:113], v1 offset:21376
	ds_read_b128 v[114:117], v1 offset:21440
	ds_read_b128 v[134:137], v1 offset:17024
	ds_read_b128 v[138:141], v1 offset:17088
	s_mulk_i32 s0, 0xa000
	v_add_u32_e32 v0, s0, v95
	ds_read_b128 v[142:145], v0
	s_waitcnt lgkmcnt(6)
	v_mfma_f32_16x16x32_bf16 v[48:51], v[48:51], v[126:129], 0
	v_add_u32_e32 v0, s14, v89
	v_add_u32_e32 v1, v0, v210
	v_cvt_pk_bf16_f32 v146, v44, v45
	s_waitcnt lgkmcnt(5)
	v_mfma_f32_16x16x32_bf16 v[48:51], v[98:101], v[130:133], v[48:51]
	ds_read_b64 v[184:185], v1 offset:25600
	ds_read_b128 v[104:107], v0 offset:33792
	v_cvt_pk_bf16_f32 v147, v46, v47
	v_cvt_pk_bf16_f32 v148, v16, v17
	s_waitcnt lgkmcnt(4)
; #define LAS __attribute__((address_space(3)))
; __device__ __forceinline__ void scan_phase(LAS unsigned char* lds, bf16* proj, int G, int bid) {
;     ...
;                 for (int i = 0; i < 4; ++i) pt = __builtin_amdgcn_mfma_f32_16x16x32_bf16(kaf[i], qbf[i], pt, 0, 0, 0);
;                 f32x4 oacc = (f32x4){0.f, 0.f, 0.f, 0.f};
; #pragma unroll
;                 for (int i = 0; i < 4; ++i) {
;                     u32x4 sw; sw.x = cvt_pk_bf16(S[2 * i][0], S[2 * i][1]); sw.y = cvt_pk_bf16(S[2 * i][2], S[2 * i][3]); sw.z = cvt_pk_bf16(S[2 * i + 1][0], S[2 * i + 1][1]); sw.w = cvt_pk_bf16(S[2 * i + 1][2], S[2 * i + 1][3]);
;                     u32x4 qw; qw.x = qlo[i][0]; qw.y = qlo[i][1]; qw.z = qhi[i][0]; qw.w = qhi[i][1];
;                     oacc = __builtin_amdgcn_mfma_f32_16x16x32_bf16(__builtin_bit_cast(bf16x8, sw), __builtin_bit_cast(bf16x8, qw), oacc, 0, 0, 0);
;                 }
;                 const LAS float* dv = (const LAS float*)(set + O_DV);
; #pragma unroll
;                 for (int kt = 0; kt < 8; ++kt) {
;                     const f32x4 d4 = *(const LAS f32x4*)(dv + kt * 16 + fq * 4);
;                     const bf16x8 ka = *(const LAS bf16x8*)(set + O_KD + (kt * 16 + fr) * 64 + fq * 16);
;                     S[kt] = __builtin_amdgcn_mfma_f32_16x16x32_bf16(ka, vf, S[kt] * d4, 0, 0, 0);
;                 }
; #pragma unroll
;                 for (int j = 0; j < 4; ++j) pt[j] = (fq * 4 + j <= fr) ? pt[j] : 0.f;
;                 u32x4 pw; pw.x = cvt_pk_bf16(pt[0], pt[1]); pw.y = cvt_pk_bf16(pt[2], pt[3]); pw.z = 0u; pw.w = 0u;
;                 oacc = __builtin_amdgcn_mfma_f32_16x16x32_bf16(vf, __builtin_bit_cast(bf16x8, pw), oacc, 0, 0, 0);
;                 __builtin_amdgcn_s_setprio(0);
	v_mfma_f32_16x16x32_bf16 v[48:51], v[110:113], v[134:137], v[48:51]
	ds_read_b128 v[108:111], v0 offset:33856
	ds_read_b64 v[188:189], v1 offset:26624
	s_waitcnt lgkmcnt(2)
	v_pk_mul_f32 v[46:47], v[46:47], v[106:107]
	v_pk_mul_f32 v[44:45], v[44:45], v[104:105]
	ds_read_b64 v[232:233], v1 offset:32768
	s_waitcnt lgkmcnt(2)
	v_pk_mul_f32 v[16:17], v[16:17], v[108:109]
	v_mfma_f32_16x16x32_bf16 v[44:47], v[184:187], v[142:145], v[44:47]
	ds_read_b64 v[192:193], v1 offset:27648
	ds_read_b128 v[106:109], v0 offset:33920
	v_cvt_pk_bf16_f32 v149, v18, v19
	v_cvt_pk_bf16_f32 v150, v20, v21
	v_cvt_pk_bf16_f32 v151, v22, v23
	v_pk_mul_f32 v[18:19], v[18:19], v[110:111]
	s_waitcnt lgkmcnt(0)
	v_pk_mul_f32 v[22:23], v[22:23], v[108:109]
	v_pk_mul_f32 v[20:21], v[20:21], v[106:107]
	v_mfma_f32_16x16x32_bf16 v[16:19], v[188:191], v[142:145], v[16:19]
	ds_read_b128 v[110:113], v0 offset:33984
	ds_read_b64 v[196:197], v1 offset:28672
	v_cvt_pk_bf16_f32 v152, v24, v25
	v_cvt_pk_bf16_f32 v153, v26, v27
	v_mfma_f32_16x16x32_bf16 v[20:23], v[192:195], v[142:145], v[20:23]
	ds_read_b64 v[200:201], v1 offset:29696
	ds_read_b128 v[106:109], v0 offset:34048
	s_waitcnt lgkmcnt(3)
	v_pk_mul_f32 v[26:27], v[26:27], v[112:113]
	v_pk_mul_f32 v[24:25], v[24:25], v[110:111]
	v_cvt_pk_bf16_f32 v154, v28, v29
	v_cvt_pk_bf16_f32 v155, v30, v31
	s_waitcnt lgkmcnt(2)
	v_mfma_f32_16x16x32_bf16 v[24:27], v[196:199], v[142:145], v[24:27]
	ds_read_b64 v[224:225], v1 offset:30720
	ds_read_b128 v[118:121], v0 offset:34112
	s_waitcnt lgkmcnt(2)
	v_pk_mul_f32 v[30:31], v[30:31], v[108:109]
	v_pk_mul_f32 v[28:29], v[28:29], v[106:107]
	v_cvt_pk_bf16_f32 v156, v32, v33
	v_cvt_pk_bf16_f32 v157, v34, v35
	v_mfma_f32_16x16x32_bf16 v[28:31], v[200:203], v[142:145], v[28:31]
	ds_read_b128 v[98:101], v0 offset:34176
	s_waitcnt lgkmcnt(1)
	v_pk_mul_f32 v[34:35], v[34:35], v[120:121]
	v_pk_mul_f32 v[32:33], v[32:33], v[118:119]
	v_cvt_pk_bf16_f32 v102, v36, v37
	v_cvt_pk_bf16_f32 v103, v38, v39
	v_mfma_f32_16x16x32_bf16 v[32:35], v[224:227], v[142:145], v[32:35]
	ds_read_b128 v[110:113], v0 offset:34240
	s_waitcnt lgkmcnt(1)
	v_pk_mul_f32 v[38:39], v[38:39], v[100:101]
	v_pk_mul_f32 v[36:37], v[36:37], v[98:99]
	v_mfma_f32_16x16x32_bf16 v[98:101], v[146:149], v[126:129], 0
	v_cvt_pk_bf16_f32 v104, v40, v41
	ds_read_b64 v[228:229], v1 offset:31744
	v_cvt_pk_bf16_f32 v105, v42, v43
	v_mfma_f32_16x16x32_bf16 v[98:101], v[150:153], v[130:133], v[98:101]
	s_waitcnt lgkmcnt(1)
	v_pk_mul_f32 v[42:43], v[42:43], v[112:113]
	v_pk_mul_f32 v[40:41], v[40:41], v[110:111]
	v_mfma_f32_16x16x32_bf16 v[48:51], v[114:117], v[138:141], v[48:51]
	v_mfma_f32_16x16x32_bf16 v[98:101], v[154:157], v[134:137], v[98:101]
	v_mfma_f32_16x16x32_bf16 v[98:101], v[102:105], v[138:141], v[98:101]
	s_nop 5
	v_cvt_pk_bf16_f32 v0, v48, s0
	v_cvt_pk_bf16_f32 v1, v49, s0
	v_cndmask_b32_e64 v0, v0, 0, s[48:49]
	v_cndmask_b32_e64 v1, 0, v1, s[50:51]
	v_perm_b32 v0, v1, v0, s11
	v_cvt_pk_bf16_f32 v1, v50, s0
	v_cvt_pk_bf16_f32 v3, v51, s0
	v_cndmask_b32_e64 v1, v1, 0, s[52:53]
	v_cndmask_b32_e64 v3, v3, 0, s[54:55]
	v_perm_b32 v1, v3, v1, s11
	v_mov_b32_e32 v3, v2
	s_waitcnt lgkmcnt(0)
	v_mfma_f32_16x16x32_bf16 v[36:39], v[228:231], v[142:145], v[36:39]
	v_mfma_f32_16x16x32_bf16 v[40:43], v[232:235], v[142:145], v[40:43]
	v_mfma_f32_16x16x32_bf16 v[48:51], v[142:145], v[0:3], v[98:101]
	s_setprio 0
	s_mov_b64 s[0:1], -1
	s_cmp_gt_u32 s6, 15
	v_add_u32_e32 v1, s4, v53
	s_cbranch_scc0 .LBB0_437
	v_add_u32_e32 v0, 0xffffff00, v1
	v_cndmask_b32_e64 v0, v96, v0, s[56:57]
	v_add_u32_e32 v0, s5, v0
	s_mov_b64 s[0:1], 0
